# baseline (speedup 1.0000x reference)
.LBB0_1498:
	s_waitcnt vmcnt(0)
	v_mov_b32_e32 v0, v131
	s_mov_b32 s2, s73
	s_mov_b32 s3, s83
	s_lshl_b32 s3, s3, 3
	s_abs_i32 s6, s3
	v_cvt_f32_u32_e32 v1, s6
	s_sub_i32 s7, 0, s6
	v_ashrrev_i32_e32 v2, 6, v0
	v_lshl_add_u32 v2, s2, 3, v2
	v_rcp_iflag_f32_e32 v1, v1
	s_add_i32 s2, s3, 0x7fff
	s_xor_b32 s3, s2, s3
	s_abs_i32 s2, s2
	v_mul_f32_e32 v1, 0x4f7ffffe, v1
	v_cvt_u32_f32_e32 v1, v1
	s_ashr_i32 s3, s3, 31
	v_readfirstlane_b32 s8, v1
	s_mul_i32 s7, s7, s8
	s_mul_hi_u32 s7, s8, s7
	s_add_i32 s8, s8, s7
	s_mul_hi_u32 s7, s2, s8
	s_mul_i32 s8, s7, s6
	s_sub_i32 s2, s2, s8
	s_add_i32 s8, s7, 1
	s_sub_i32 s9, s2, s6
	s_cmp_ge_u32 s2, s6
	s_cselect_b32 s7, s8, s7
	s_cselect_b32 s2, s9, s2
	s_add_i32 s8, s7, 1
	s_cmp_ge_u32 s2, s6
	s_cselect_b32 s2, s8, s7
	s_xor_b32 s2, s2, s3
	s_sub_i32 s2, s2, s3
	s_add_i32 s2, s2, 3
	s_and_b32 s2, s2, -4
	v_mul_lo_u32 v64, s2, v2
	v_add_u32_e32 v1, s2, v64
	v_min_i32_e32 v67, 0x8000, v1
	v_cmp_lt_i32_e32 vcc, v64, v67
	s_and_saveexec_b64 s[2:3], vcc
	s_cbranch_execz .LBB0_1526
	v_readlane_b32 s42, v255, 20
	s_add_i32 s34, s42, 1
	s_mul_i32 s7, s34, 0x18000
	v_readlane_b32 s8, v255, 15
	s_mul_hi_i32 s6, s34, 0x18000
	v_readlane_b32 s9, v255, 16
	s_add_u32 s12, s8, s7
	s_addc_u32 s13, s9, s6
	s_cmp_lt_i32 s42, 3
	s_waitcnt lgkmcnt(0)
	s_cselect_b64 s[14:15], -1, 0
	s_add_u32 s22, s12, 0x1000
	s_addc_u32 s23, s13, 0
	s_add_u32 s38, s26, 0x3981000
	s_addc_u32 s39, s27, 0
	s_add_u32 s40, s26, 0x3c00000
	s_addc_u32 s41, s27, 0
	s_and_b64 s[36:37], s[10:11], exec
	s_load_dwordx2 s[6:7], s[0:1], 0x20
	s_load_dwordx2 s[8:9], s[0:1], 0x38
	s_load_dwordx2 s[18:19], s[0:1], 0x98
	s_cselect_b32 s37, s41, 0
	s_cselect_b32 s36, s40, 0
	s_lshl_b32 s40, s34, 10
	s_ashr_i32 s41, s40, 31
	s_lshl_b64 s[40:41], s[40:41], 2
	s_waitcnt lgkmcnt(0)
	s_add_u32 s6, s6, s40
	s_addc_u32 s7, s7, s41
	v_lshlrev_b32_e32 v1, 2, v0
	s_and_b64 s[40:41], s[14:15], exec
	v_and_b32_e32 v66, 0xfc, v1
	s_cselect_b32 s47, s17, 0
	s_cselect_b32 s46, s16, 0
	s_lshl_b32 s40, s42, 10
	v_lshlrev_b32_e32 v128, 2, v66
	s_ashr_i32 s41, s40, 31
	v_lshl_add_u64 v[70:71], s[6:7], 0, v[128:129]
	v_readlane_b32 s6, v255, 18
	s_lshl_b64 s[40:41], s[40:41], 2
	v_readlane_b32 s7, v255, 19
	s_add_u32 s8, s8, s40
	v_ashrrev_i32_e32 v65, 31, v64
	v_lshl_add_u64 v[2:3], s[6:7], 0, v[128:129]
	s_mov_b64 s[6:7], 0x5000
	s_addc_u32 s9, s9, s41
	v_lshl_add_u64 v[74:75], v[2:3], 0, s[6:7]
	v_lshlrev_b64 v[2:3], 12, v[64:65]
	v_and_b32_e32 v4, 63, v0
	v_readlane_b32 s43, v255, 21
	s_cmp_lg_u64 s[46:47], 0
	v_lshl_or_b32 v2, v4, 4, v2
	s_cselect_b64 s[42:43], -1, 0
	s_cmp_lg_u64 s[36:37], 0
	v_lshl_add_u64 v[0:1], s[24:25], 0, v[2:3]
	s_mov_b64 s[6:7], 0x1000
	s_cselect_b64 s[68:69], -1, 0
	s_cmp_lg_u64 s[24:25], 0
	v_lshl_add_u64 v[76:77], v[0:1], 0, s[6:7]
	v_lshlrev_b64 v[0:1], 11, v[64:65]
	v_mov_b32_e32 v86, 0
	s_movk_i32 s34, 0x2000
	s_mov_b64 s[40:41], 0
	s_cselect_b64 s[70:71], -1, 0
	v_lshl_add_u64 v[68:69], s[8:9], 0, v[128:129]
	v_lshl_add_u64 v[72:73], s[18:19], 0, v[128:129]
	v_lshlrev_b32_e32 v78, 3, v4
	v_mov_b32_e32 v79, v129
	v_lshl_add_u64 v[80:81], s[26:27], 0, v[0:1]
	v_lshl_add_u64 v[82:83], s[36:37], 0, v[0:1]
	v_lshl_add_u64 v[84:85], s[46:47], 0, v[0:1]
	v_mov_b32_e32 v65, -1
	v_mov_b32_e32 v87, v86
	v_mov_b32_e32 v106, v86
	v_mov_b32_e32 v107, v86
	v_mov_b32_e32 v104, v86
	v_mov_b32_e32 v105, v86
	v_mov_b32_e32 v110, v86
	v_mov_b32_e32 v111, v86
	v_mov_b32_e32 v108, v86
	v_mov_b32_e32 v109, v86
	v_mov_b32_e32 v114, v86
	v_mov_b32_e32 v115, v86
	v_mov_b32_e32 v112, v86
	v_mov_b32_e32 v113, v86
	v_mov_b32_e32 v116, v86
	v_mov_b32_e32 v117, v86
	s_mov_b32 s100, 0
	s_branch .LBB0_1501

.LBB0_1519:
	s_or_b64 exec, exec, s[24:25]
	v_lshl_add_u64 v[138:139], v[80:81], 0, v[78:79]
	s_mov_b32 s6, 0xec00000
	v_add_co_u32_e32 v138, vcc, s6, v138
	s_nop 1
	v_addc_co_u32_e32 v139, vcc, 0, v139, vcc
	s_cmp_eq_u32 s100, 0
	s_cbranch_scc0 .Leb_have
	global_load_dwordx4 v[60:63], v[76:77], off offset:-4096 nt
	global_load_dwordx4 v[56:59], v[76:77], off offset:-3072 nt
	global_load_dwordx4 v[52:55], v[76:77], off offset:-2048 nt
	global_load_dwordx4 v[48:51], v[76:77], off offset:-1024 nt
	global_load_dwordx4 v[44:47], v[76:77], off nt
	global_load_dwordx4 v[40:43], v[76:77], off offset:1024 nt
	global_load_dwordx4 v[36:39], v[76:77], off offset:2048 nt
	global_load_dwordx4 v[32:35], v[76:77], off offset:3072 nt
	global_load_dwordx2 v[140:141], v[138:139], off nt
	global_load_dwordx2 v[144:145], v[138:139], off offset:512 nt
	global_load_dwordx2 v[148:149], v[138:139], off offset:1024 nt
	global_load_dwordx2 v[152:153], v[138:139], off offset:1536 nt
	global_load_dwordx2 v[160:161], v[138:139], off offset:2048 nt
	global_load_dwordx2 v[166:167], v[138:139], off offset:2560 nt
	global_load_dwordx2 v[168:169], v[138:139], off offset:3072 nt
	global_load_dwordx2 v[162:163], v[138:139], off offset:3584 nt
	s_mov_b32 s100, 1
	s_waitcnt vmcnt(0)
	s_branch .Leb_pref
.Leb_have:
	s_waitcnt vmcnt(8)
	v_mov_b64 v[32:33], v[194:195]
	v_mov_b64 v[34:35], v[196:197]
	v_mov_b64 v[36:37], v[198:199]
	v_mov_b64 v[38:39], v[200:201]
	v_mov_b64 v[40:41], v[202:203]
	v_mov_b64 v[42:43], v[204:205]
	v_mov_b64 v[44:45], v[206:207]
	v_mov_b64 v[46:47], v[208:209]
	v_mov_b64 v[48:49], v[210:211]
	v_mov_b64 v[50:51], v[212:213]
	v_mov_b64 v[52:53], v[214:215]
	v_mov_b64 v[54:55], v[216:217]
	v_mov_b64 v[56:57], v[218:219]
	v_mov_b64 v[58:59], v[220:221]
	v_mov_b64 v[60:61], v[222:223]
	v_mov_b64 v[62:63], v[224:225]
	v_mov_b64 v[140:141], v[226:227]
	v_mov_b64 v[144:145], v[228:229]
	v_mov_b64 v[148:149], v[230:231]
	v_mov_b64 v[152:153], v[232:233]
	v_mov_b64 v[160:161], v[234:235]
	v_mov_b64 v[166:167], v[236:237]
	v_mov_b64 v[168:169], v[238:239]
	v_mov_b64 v[162:163], v[240:241]
.Leb_pref:
	v_add_u32_e32 v246, 2, v64
	v_cmp_lt_i32_e32 vcc, v246, v67
	s_cbranch_vccz .Leb_nopref
	s_mov_b64 s[6:7], 0x2000
	v_lshl_add_u64 v[242:243], v[76:77], 0, s[6:7]
	s_mov_b64 s[6:7], 0x1000
	v_lshl_add_u64 v[244:245], v[138:139], 0, s[6:7]
	global_load_dwordx4 v[222:225], v[242:243], off offset:-4096 nt
	global_load_dwordx4 v[218:221], v[242:243], off offset:-3072 nt
	global_load_dwordx4 v[214:217], v[242:243], off offset:-2048 nt
	global_load_dwordx4 v[210:213], v[242:243], off offset:-1024 nt
	global_load_dwordx4 v[206:209], v[242:243], off nt
	global_load_dwordx4 v[202:205], v[242:243], off offset:1024 nt
	global_load_dwordx4 v[198:201], v[242:243], off offset:2048 nt
	global_load_dwordx4 v[194:197], v[242:243], off offset:3072 nt
	global_load_dwordx2 v[226:227], v[244:245], off nt
	global_load_dwordx2 v[228:229], v[244:245], off offset:512 nt
	global_load_dwordx2 v[230:231], v[244:245], off offset:1024 nt
	global_load_dwordx2 v[232:233], v[244:245], off offset:1536 nt
	global_load_dwordx2 v[234:235], v[244:245], off offset:2048 nt
	global_load_dwordx2 v[236:237], v[244:245], off offset:2560 nt
	global_load_dwordx2 v[238:239], v[244:245], off offset:3072 nt
	global_load_dwordx2 v[240:241], v[244:245], off offset:3584 nt
.Leb_nopref:
	s_mov_b32 s6, 0x3a800000
	v_lshlrev_b32_e32 v138, 16, v140
	v_and_b32_e32 v139, 0xffff0000, v140
	v_pk_mul_f32 v[154:155], v[138:139], v[138:139]
	v_lshlrev_b32_e32 v140, 16, v141
	v_and_b32_e32 v141, 0xffff0000, v141
	v_pk_mul_f32 v[156:157], v[140:141], v[140:141]
	v_add_f32_e32 v128, v154, v155
	v_lshlrev_b32_e32 v142, 16, v144
	v_and_b32_e32 v143, 0xffff0000, v144
	v_add_f32_e32 v128, v156, v128
	v_pk_mul_f32 v[158:159], v[142:143], v[142:143]
	v_add_f32_e32 v128, v157, v128
	v_lshlrev_b32_e32 v144, 16, v145
	v_and_b32_e32 v145, 0xffff0000, v145
	v_add_f32_e32 v128, v158, v128
	v_pk_mul_f32 v[164:165], v[144:145], v[144:145]
	v_add_f32_e32 v128, v159, v128
	v_lshlrev_b32_e32 v146, 16, v148
	v_and_b32_e32 v147, 0xffff0000, v148
	v_add_f32_e32 v128, v164, v128
	v_pk_mul_f32 v[170:171], v[146:147], v[146:147]
	v_add_f32_e32 v128, v165, v128
	v_lshlrev_b32_e32 v148, 16, v149
	v_and_b32_e32 v149, 0xffff0000, v149
	v_add_f32_e32 v128, v170, v128
	v_pk_mul_f32 v[172:173], v[148:149], v[148:149]
	v_add_f32_e32 v128, v171, v128
	v_lshlrev_b32_e32 v150, 16, v152
	v_and_b32_e32 v151, 0xffff0000, v152
	v_add_f32_e32 v128, v172, v128
	v_pk_mul_f32 v[178:179], v[150:151], v[150:151]
	v_add_f32_e32 v128, v173, v128
	v_lshlrev_b32_e32 v152, 16, v153
	v_and_b32_e32 v153, 0xffff0000, v153
	v_add_f32_e32 v128, v178, v128
	v_pk_mul_f32 v[180:181], v[152:153], v[152:153]
	v_add_f32_e32 v128, v179, v128
	v_add_f32_e32 v128, v180, v128
	v_add_f32_e32 v128, v181, v128
	v_lshlrev_b32_e32 v158, 16, v160
	v_and_b32_e32 v159, 0xffff0000, v160
	v_add_f32_dpp v128, v128, v128 quad_perm:[1,0,3,2] row_mask:0xf bank_mask:0xf bound_ctrl:1
	v_pk_mul_f32 v[178:179], v[158:159], v[158:159]
	v_lshlrev_b32_e32 v160, 16, v161
	v_add_f32_dpp v128, v128, v128 quad_perm:[2,3,0,1] row_mask:0xf bank_mask:0xf bound_ctrl:1
	v_and_b32_e32 v161, 0xffff0000, v161
	v_pk_mul_f32 v[180:181], v[160:161], v[160:161]
	v_add_f32_dpp v128, v128, v128 row_half_mirror row_mask:0xf bank_mask:0xf bound_ctrl:1
	v_lshlrev_b32_e32 v164, 16, v166
	v_and_b32_e32 v165, 0xffff0000, v166
	v_add_f32_dpp v128, v128, v128 row_mirror row_mask:0xf bank_mask:0xf bound_ctrl:1
	v_mov_b32_e32 v154, v128
	s_nop 1
	v_permlane16_swap_b32_e32 v128, v154
	v_add_f32_e32 v155, v128, v154
	v_add_f32_e32 v128, v178, v179
	v_add_f32_e32 v128, v180, v128
	v_pk_mul_f32 v[182:183], v[164:165], v[164:165]
	v_add_f32_e32 v128, v181, v128
	v_lshlrev_b32_e32 v166, 16, v167
	v_and_b32_e32 v167, 0xffff0000, v167
	v_add_f32_e32 v128, v182, v128
	v_pk_mul_f32 v[184:185], v[166:167], v[166:167]
	v_add_f32_e32 v128, v183, v128
	v_lshlrev_b32_e32 v170, 16, v168
	v_and_b32_e32 v171, 0xffff0000, v168
	v_add_f32_e32 v128, v184, v128
	v_pk_mul_f32 v[186:187], v[170:171], v[170:171]
	v_add_f32_e32 v128, v185, v128
	v_lshlrev_b32_e32 v168, 16, v169
	v_and_b32_e32 v169, 0xffff0000, v169
	v_add_f32_e32 v128, v186, v128
	v_pk_mul_f32 v[188:189], v[168:169], v[168:169]
	v_add_f32_e32 v128, v187, v128
	v_lshlrev_b32_e32 v172, 16, v162
	v_and_b32_e32 v173, 0xffff0000, v162
	v_add_f32_e32 v128, v188, v128
	v_pk_mul_f32 v[190:191], v[172:173], v[172:173]
	v_add_f32_e32 v128, v189, v128
	v_lshlrev_b32_e32 v162, 16, v163
	v_and_b32_e32 v163, 0xffff0000, v163
	v_add_f32_e32 v128, v190, v128
	v_pk_mul_f32 v[192:193], v[162:163], v[162:163]
	v_add_f32_e32 v128, v191, v128
	v_add_f32_e32 v128, v192, v128
	v_add_f32_e32 v128, v193, v128
	v_mov_b32_e32 v157, v155
	s_nop 1
	v_permlane32_swap_b32_e32 v155, v157
	v_add_f32_dpp v128, v128, v128 quad_perm:[1,0,3,2] row_mask:0xf bank_mask:0xf bound_ctrl:1
	v_pk_mul_f32 v[138:139], v[134:135], v[138:139]
	v_pk_mul_f32 v[140:141], v[136:137], v[140:141]
	v_add_f32_dpp v128, v128, v128 quad_perm:[2,3,0,1] row_mask:0xf bank_mask:0xf bound_ctrl:1
	v_pk_mul_f32 v[142:143], v[126:127], v[142:143]
	v_pk_mul_f32 v[144:145], v[132:133], v[144:145]
	v_add_f32_dpp v128, v128, v128 row_half_mirror row_mask:0xf bank_mask:0xf bound_ctrl:1
	v_pk_mul_f32 v[146:147], v[122:123], v[146:147]
	v_pk_mul_f32 v[148:149], v[124:125], v[148:149]
	v_add_f32_dpp v128, v128, v128 row_mirror row_mask:0xf bank_mask:0xf bound_ctrl:1
	v_mov_b32_e32 v154, v128
	s_nop 1
	v_permlane16_swap_b32_e32 v128, v154
	v_add_f32_e32 v154, v128, v154
	v_mov_b32_e32 v156, v154
	s_nop 1
	v_permlane32_swap_b32_e32 v154, v156
	v_pk_add_f32 v[154:155], v[154:155], v[156:157]
	v_pk_mul_f32 v[150:151], v[118:119], v[150:151]
	v_pk_fma_f32 v[154:155], v[154:155], s[6:7], v[130:131] op_sel_hi:[1,0,0]
	v_pk_mul_f32 v[152:153], v[120:121], v[152:153]
	v_mul_f32_e32 v128, 0x4b800000, v155
	v_cmp_gt_f32_e64 s[6:7], s89, v155
	v_cmp_gt_f32_e32 vcc, s89, v154
	v_pk_mul_f32 v[158:159], v[134:135], v[158:159]
	v_cndmask_b32_e64 v128, v155, v128, s[6:7]
	v_rsq_f32_e32 v128, v128
	v_pk_mul_f32 v[160:161], v[136:137], v[160:161]
	v_pk_mul_f32 v[164:165], v[126:127], v[164:165]
	v_pk_mul_f32 v[166:167], v[132:133], v[166:167]
	v_mul_f32_e32 v155, 0x45800000, v128
	v_cndmask_b32_e64 v128, v128, v155, s[6:7]
	v_pk_fma_f32 v[60:61], v[138:139], v[128:129], v[60:61] op_sel_hi:[1,0,1]
	v_pk_fma_f32 v[62:63], v[140:141], v[128:129], v[62:63] op_sel_hi:[1,0,1]
	v_pk_fma_f32 v[56:57], v[142:143], v[128:129], v[56:57] op_sel_hi:[1,0,1]
	v_pk_fma_f32 v[58:59], v[144:145], v[128:129], v[58:59] op_sel_hi:[1,0,1]
	v_pk_fma_f32 v[52:53], v[146:147], v[128:129], v[52:53] op_sel_hi:[1,0,1]
	v_pk_fma_f32 v[54:55], v[148:149], v[128:129], v[54:55] op_sel_hi:[1,0,1]
	v_pk_fma_f32 v[48:49], v[150:151], v[128:129], v[48:49] op_sel_hi:[1,0,1]
	v_pk_fma_f32 v[50:51], v[152:153], v[128:129], v[50:51] op_sel_hi:[1,0,1]
	v_mul_f32_e32 v128, 0x4b800000, v154
	v_cndmask_b32_e32 v128, v154, v128, vcc
	v_rsq_f32_e32 v128, v128
	v_pk_mul_f32 v[170:171], v[122:123], v[170:171]
	v_pk_mul_f32 v[168:169], v[124:125], v[168:169]
	v_pk_mul_f32 v[172:173], v[118:119], v[172:173]
	v_mul_f32_e32 v138, 0x45800000, v128
	v_cndmask_b32_e32 v128, v128, v138, vcc
	v_pk_mul_f32 v[138:139], v[120:121], v[162:163]
	v_pk_fma_f32 v[44:45], v[158:159], v[128:129], v[44:45] op_sel_hi:[1,0,1]
	v_pk_fma_f32 v[46:47], v[160:161], v[128:129], v[46:47] op_sel_hi:[1,0,1]
	v_pk_fma_f32 v[40:41], v[164:165], v[128:129], v[40:41] op_sel_hi:[1,0,1]
	v_pk_fma_f32 v[42:43], v[166:167], v[128:129], v[42:43] op_sel_hi:[1,0,1]
	v_pk_fma_f32 v[36:37], v[170:171], v[128:129], v[36:37] op_sel_hi:[1,0,1]
	v_pk_fma_f32 v[38:39], v[168:169], v[128:129], v[38:39] op_sel_hi:[1,0,1]
	v_pk_fma_f32 v[32:33], v[172:173], v[128:129], v[32:33] op_sel_hi:[1,0,1]
	v_pk_fma_f32 v[34:35], v[138:139], v[128:129], v[34:35] op_sel_hi:[1,0,1]
	s_andn2_b64 vcc, exec, s[70:71]
	s_cbranch_vccnz .LBB0_1521
	global_store_dwordx4 v[76:77], v[60:63], off offset:-4096 nt
	global_store_dwordx4 v[76:77], v[56:59], off offset:-3072 nt
	global_store_dwordx4 v[76:77], v[52:55], off offset:-2048 nt
	global_store_dwordx4 v[76:77], v[48:51], off offset:-1024 nt
	global_store_dwordx4 v[76:77], v[44:47], off nt
	global_store_dwordx4 v[76:77], v[40:43], off offset:1024 nt
	global_store_dwordx4 v[76:77], v[36:39], off offset:2048 nt
	global_store_dwordx4 v[76:77], v[32:35], off offset:3072 nt

	.amdhsa_kernel _Z8yoco_fwd6Params
		.amdhsa_group_segment_fixed_size 131072
		.amdhsa_private_segment_fixed_size 0
		.amdhsa_kernarg_size 488
		.amdhsa_user_sgpr_count 2
		.amdhsa_user_sgpr_dispatch_ptr 0
		.amdhsa_user_sgpr_queue_ptr 0
		.amdhsa_user_sgpr_kernarg_segment_ptr 1
		.amdhsa_user_sgpr_dispatch_id 0
		.amdhsa_user_sgpr_kernarg_preload_length 0
		.amdhsa_user_sgpr_kernarg_preload_offset 0
		.amdhsa_user_sgpr_private_segment_size 0
		.amdhsa_uses_dynamic_stack 0
		.amdhsa_enable_private_segment 0
		.amdhsa_system_sgpr_workgroup_id_x 1
		.amdhsa_system_sgpr_workgroup_id_y 0
		.amdhsa_system_sgpr_workgroup_id_z 0
		.amdhsa_system_sgpr_workgroup_info 0
		.amdhsa_system_vgpr_workitem_id 2
		.amdhsa_next_free_vgpr 256
		.amdhsa_next_free_sgpr 102
		.amdhsa_accum_offset 256
		.amdhsa_reserve_vcc 1
		.amdhsa_float_round_mode_32 0
		.amdhsa_float_round_mode_16_64 0
		.amdhsa_float_denorm_mode_32 3
		.amdhsa_float_denorm_mode_16_64 3
		.amdhsa_dx10_clamp 1
		.amdhsa_ieee_mode 1
		.amdhsa_fp16_overflow 0
		.amdhsa_tg_split 0
		.amdhsa_exception_fp_ieee_invalid_op 0
		.amdhsa_exception_fp_denorm_src 0
		.amdhsa_exception_fp_ieee_div_zero 0
		.amdhsa_exception_fp_ieee_overflow 0
		.amdhsa_exception_fp_ieee_underflow 0
		.amdhsa_exception_fp_ieee_inexact 0
		.amdhsa_exception_int_div_zero 0
	.end_amdhsa_kernel

amdhsa.kernels:
  - .agpr_count:     0
    .args:
      - .offset:         0
        .size:           232
        .value_kind:     by_value
      - .offset:         232
        .size:           4
        .value_kind:     hidden_block_count_x
      - .offset:         236
        .size:           4
        .value_kind:     hidden_block_count_y
      - .offset:         240
        .size:           4
        .value_kind:     hidden_block_count_z
      - .offset:         244
        .size:           2
        .value_kind:     hidden_group_size_x
      - .offset:         246
        .size:           2
        .value_kind:     hidden_group_size_y
      - .offset:         248
        .size:           2
        .value_kind:     hidden_group_size_z
      - .offset:         250
        .size:           2
        .value_kind:     hidden_remainder_x
      - .offset:         252
        .size:           2
        .value_kind:     hidden_remainder_y
      - .offset:         254
        .size:           2
        .value_kind:     hidden_remainder_z
      - .offset:         272
        .size:           8
        .value_kind:     hidden_global_offset_x
      - .offset:         280
        .size:           8
        .value_kind:     hidden_global_offset_y
      - .offset:         288
        .size:           8
        .value_kind:     hidden_global_offset_z
      - .offset:         296
        .size:           2
        .value_kind:     hidden_grid_dims
      - .offset:         320
        .size:           8
        .value_kind:     hidden_multigrid_sync_arg
    .group_segment_fixed_size: 131072
    .kernarg_segment_align: 8
    .kernarg_segment_size: 488
    .language:       OpenCL C
    .language_version:
      - 2
      - 0
    .max_flat_workgroup_size: 512
    .name:           _Z8yoco_fwd6Params
    .private_segment_fixed_size: 0
    .sgpr_count:     108
    .sgpr_spill_count: 39
    .symbol:         _Z8yoco_fwd6Params.kd
    .uniform_work_group_size: 1
    .uses_dynamic_stack: false
    .vgpr_count:     256
    .vgpr_spill_count: 0
    .wavefront_size: 64
